# attention: row-sum chain split (4 partial sums) + delete 24 provably redundant lgkmcnt waits before QK MFMAs in main loops
# speedup vs baseline: 1.0106x; 1.0015x over previous
.LBB0_1258:
	s_mov_b32 s73, s61
	s_mov_b32 s43, s60
	v_add_u32_e32 v0, s43, v247
	ds_read_b64_tr_b16 v[220:221], v0 offset:49152
	ds_read_b64_tr_b16 v[222:223], v0 offset:49664
	v_mfma_f32_32x32x16_bf16 v[128:143], v[112:115], v[180:183], v[64:79]
	v_add_f32_e32 v250, v96, v97
	v_add_f32_e32 v251, v98, v99
	v_add_f32_e32 v252, v100, v101
	v_add_f32_e32 v253, v102, v103
	v_add_f32_e32 v250, v104, v250
	v_cvt_pk_bf16_f32 v184, v96, v97
	v_cvt_pk_bf16_f32 v185, v98, v99
	ds_read_b64_tr_b16 v[216:217], v0 offset:53248
	ds_read_b64_tr_b16 v[218:219], v0 offset:53760
	v_mfma_f32_32x32x16_bf16 v[112:127], v[208:211], v[180:183], v[64:79]
	v_add_f32_e32 v251, v105, v251
	v_add_f32_e32 v252, v106, v252
	v_add_f32_e32 v253, v107, v253
	v_add_f32_e32 v250, v108, v250
	v_cvt_pk_bf16_f32 v186, v100, v101
	v_cvt_pk_bf16_f32 v187, v102, v103
	ds_read_b64_tr_b16 v[96:97], v0 offset:50176
	ds_read_b64_tr_b16 v[98:99], v0 offset:50688
	v_mfma_f32_32x32x16_bf16 v[128:143], v[212:215], v[176:179], v[128:143]
	v_add_f32_e32 v251, v109, v251
	v_add_f32_e32 v252, v110, v252
	v_add_f32_e32 v253, v111, v253
	v_add_f32_e32 v250, v80, v250
	v_cvt_pk_bf16_f32 v10, v104, v105
	v_cvt_pk_bf16_f32 v11, v106, v107
	ds_read_b64_tr_b16 v[100:101], v0 offset:54272
	ds_read_b64_tr_b16 v[102:103], v0 offset:54784
	v_mfma_f32_32x32x16_bf16 v[112:127], v[204:207], v[176:179], v[112:127]
	v_add_f32_e32 v251, v81, v251
	v_add_f32_e32 v252, v82, v252
	v_add_f32_e32 v253, v83, v253
	v_add_f32_e32 v250, v84, v250
	v_cvt_pk_bf16_f32 v12, v108, v109
	v_cvt_pk_bf16_f32 v13, v110, v111
	ds_read_b64_tr_b16 v[104:105], v0 offset:51200
	ds_read_b64_tr_b16 v[106:107], v0 offset:51712
	v_mfma_f32_32x32x16_bf16 v[128:143], v[200:203], v[172:175], v[128:143]
	v_add_f32_e32 v251, v85, v251
	v_add_f32_e32 v252, v86, v252
	v_add_f32_e32 v253, v87, v253
	v_add_f32_e32 v250, v88, v250
	v_cvt_pk_bf16_f32 v6, v80, v81
	v_cvt_pk_bf16_f32 v7, v82, v83
	ds_read_b64_tr_b16 v[80:81], v0 offset:55296
	ds_read_b64_tr_b16 v[82:83], v0 offset:55808
	v_mfma_f32_32x32x16_bf16 v[112:127], v[196:199], v[172:175], v[112:127]
	v_add_f32_e32 v251, v89, v251
	v_add_f32_e32 v252, v90, v252
	v_add_f32_e32 v253, v91, v253
	v_add_f32_e32 v250, v92, v250
	v_cvt_pk_bf16_f32 v8, v84, v85
	v_cvt_pk_bf16_f32 v9, v86, v87
	ds_read_b64_tr_b16 v[84:85], v0 offset:52224
	ds_read_b64_tr_b16 v[86:87], v0 offset:52736
	v_mfma_f32_32x32x16_bf16 v[128:143], v[192:195], v[168:171], v[128:143]
	v_add_f32_e32 v251, v93, v251
	v_add_f32_e32 v252, v94, v252
	v_add_f32_e32 v253, v95, v253
	v_add_f32_e32 v250, v251, v250
	v_cvt_pk_bf16_f32 v2, v88, v89
	v_cvt_pk_bf16_f32 v3, v90, v91
	ds_read_b64_tr_b16 v[88:89], v0 offset:56320
	ds_read_b64_tr_b16 v[90:91], v0 offset:56832
	v_mfma_f32_32x32x16_bf16 v[112:127], v[188:191], v[168:171], v[112:127]
	v_add_f32_e32 v252, v253, v252
	v_add_f32_e32 v0, v252, v250
	v_cvt_pk_bf16_f32 v4, v92, v93
	v_cvt_pk_bf16_f32 v5, v94, v95
	v_mfma_f32_32x32x16_bf16 v[128:143], v[148:151], v[164:167], v[128:143]
	v_mfma_f32_32x32x16_bf16 v[112:127], v[144:147], v[164:167], v[112:127]
	v_mfma_f32_32x32x16_bf16 v[128:143], v[156:159], v[160:163], v[128:143]
	v_mfma_f32_32x32x16_bf16 v[112:127], v[152:155], v[160:163], v[112:127]
	s_lshr_b32 s60, s61, 1
	s_add_i32 s60, s60, s61
	s_add_i32 s61, s60, s47
	s_mov_b32 s62, m0
	s_mov_b32 m0, s61
	s_nop 0
	global_load_lds_dwordx4 v[230:231], off
	s_mov_b32 m0, s62
	s_and_b64 vcc, exec, s[6:7]
	s_cbranch_vccnz .LBB0_1260
	v_lshl_add_u64 v[14:15], s[30:31], 1, v[230:231]
	s_add_i32 s60, s60, s67
	v_lshl_add_u64 v[14:15], v[14:15], 0, s[10:11]
	s_mov_b32 s61, m0
	s_mov_b32 m0, s60
	s_nop 0
	global_load_lds_dwordx4 v[14:15], off
	s_mov_b32 m0, s61

.LBB0_1265:
	v_add_u32_e32 v14, s73, v247
	ds_read_b64_tr_b16 v[148:149], v14 offset:49152
	ds_read_b64_tr_b16 v[150:151], v14 offset:49664
	v_mfma_f32_32x32x16_bf16 v[96:111], v[92:95], v[180:183], v[64:79]
	v_add_f32_e32 v250, v128, v129
	v_add_f32_e32 v251, v130, v131
	v_add_f32_e32 v252, v132, v133
	v_add_f32_e32 v253, v134, v135
	v_add_f32_e32 v250, v136, v250
	v_cvt_pk_bf16_f32 v184, v128, v129
	v_cvt_pk_bf16_f32 v185, v130, v131
	ds_read_b64_tr_b16 v[144:145], v14 offset:53248
	ds_read_b64_tr_b16 v[146:147], v14 offset:53760
	v_mfma_f32_32x32x16_bf16 v[80:95], v[216:219], v[180:183], v[64:79]
	v_add_f32_e32 v251, v137, v251
	v_add_f32_e32 v252, v138, v252
	v_add_f32_e32 v253, v139, v253
	v_add_f32_e32 v250, v140, v250
	v_cvt_pk_bf16_f32 v186, v132, v133
	v_cvt_pk_bf16_f32 v187, v134, v135
	ds_read_b64_tr_b16 v[128:129], v14 offset:50176
	ds_read_b64_tr_b16 v[130:131], v14 offset:50688
	v_mfma_f32_32x32x16_bf16 v[96:111], v[220:223], v[176:179], v[96:111]
	v_add_f32_e32 v251, v141, v251
	v_add_f32_e32 v252, v142, v252
	v_add_f32_e32 v253, v143, v253
	v_add_f32_e32 v250, v112, v250
	v_cvt_pk_bf16_f32 v10, v136, v137
	v_cvt_pk_bf16_f32 v11, v138, v139
	ds_read_b64_tr_b16 v[132:133], v14 offset:54272
	ds_read_b64_tr_b16 v[134:135], v14 offset:54784
	v_mfma_f32_32x32x16_bf16 v[80:95], v[212:215], v[176:179], v[80:95]
	v_add_f32_e32 v251, v113, v251
	v_add_f32_e32 v252, v114, v252
	v_add_f32_e32 v253, v115, v253
	v_add_f32_e32 v250, v116, v250
	v_cvt_pk_bf16_f32 v12, v140, v141
	v_cvt_pk_bf16_f32 v13, v142, v143
	ds_read_b64_tr_b16 v[136:137], v14 offset:51200
	ds_read_b64_tr_b16 v[138:139], v14 offset:51712
	v_mfma_f32_32x32x16_bf16 v[96:111], v[208:211], v[172:175], v[96:111]
	v_add_f32_e32 v251, v117, v251
	v_add_f32_e32 v252, v118, v252
	v_add_f32_e32 v253, v119, v253
	v_add_f32_e32 v250, v120, v250
	v_cvt_pk_bf16_f32 v6, v112, v113
	v_cvt_pk_bf16_f32 v7, v114, v115
	ds_read_b64_tr_b16 v[140:141], v14 offset:55296
	ds_read_b64_tr_b16 v[142:143], v14 offset:55808
	v_mfma_f32_32x32x16_bf16 v[80:95], v[204:207], v[172:175], v[80:95]
	v_add_f32_e32 v251, v121, v251
	v_add_f32_e32 v252, v122, v252
	v_add_f32_e32 v253, v123, v253
	v_add_f32_e32 v250, v124, v250
	v_cvt_pk_bf16_f32 v8, v116, v117
	v_cvt_pk_bf16_f32 v9, v118, v119
	ds_read_b64_tr_b16 v[116:117], v14 offset:52224
	ds_read_b64_tr_b16 v[118:119], v14 offset:52736
	v_mfma_f32_32x32x16_bf16 v[96:111], v[200:203], v[168:171], v[96:111]
	v_add_f32_e32 v251, v125, v251
	v_add_f32_e32 v252, v126, v252
	v_add_f32_e32 v253, v127, v253
	v_add_f32_e32 v250, v251, v250
	v_cvt_pk_bf16_f32 v2, v120, v121
	v_cvt_pk_bf16_f32 v3, v122, v123
	ds_read_b64_tr_b16 v[120:121], v14 offset:56320
	ds_read_b64_tr_b16 v[122:123], v14 offset:56832
	v_mfma_f32_32x32x16_bf16 v[80:95], v[156:159], v[168:171], v[80:95]
	v_add_f32_e32 v252, v253, v252
	v_add_f32_e32 v112, v252, v250
	v_cvt_pk_bf16_f32 v4, v124, v125
	v_cvt_pk_bf16_f32 v5, v126, v127
	v_mfma_f32_32x32x16_bf16 v[96:111], v[188:191], v[164:167], v[96:111]
	v_mfma_f32_32x32x16_bf16 v[80:95], v[152:155], v[164:167], v[80:95]
	v_mfma_f32_32x32x16_bf16 v[96:111], v[196:199], v[160:163], v[96:111]
	v_mfma_f32_32x32x16_bf16 v[80:95], v[192:195], v[160:163], v[80:95]
	v_lshl_add_u64 v[14:15], v[230:231], 0, s[12:13]
	s_add_i32 s60, s66, s47
	s_mov_b32 s61, m0
	s_mov_b32 m0, s60
	s_nop 0
	global_load_lds_dwordx4 v[14:15], off
	s_mov_b32 m0, s61
	s_and_b64 vcc, exec, s[6:7]
	s_cbranch_vccnz .LBB0_1267
	v_lshl_add_u64 v[14:15], s[30:31], 1, v[14:15]
	s_add_i32 s60, s66, s67
	v_lshl_add_u64 v[14:15], v[14:15], 0, s[10:11]
	s_mov_b32 s61, m0
	s_mov_b32 m0, s60
	s_nop 0
	global_load_lds_dwordx4 v[14:15], off
	s_mov_b32 m0, s61

.LBB0_1313:
	s_mov_b32 s6, s47
	s_mov_b32 s7, s46
	v_add_u32_e32 v214, s7, v206
	ds_read_b64_tr_b16 v[210:211], v214 offset:32768
	ds_read_b64_tr_b16 v[212:213], v214 offset:33280
	v_add_f32_e32 v250, v96, v97
	v_add_f32_e32 v251, v98, v99
	v_add_f32_e32 v252, v100, v101
	v_add_f32_e32 v253, v102, v103
	v_add_f32_e32 v250, v104, v250
	v_cvt_pk_bf16_f32 v160, v96, v97
	v_cvt_pk_bf16_f32 v161, v98, v99
	v_mfma_f32_32x32x16_bf16 v[128:143], v[112:115], v[172:175], v[32:47]
	ds_read_b64_tr_b16 v[96:97], v214 offset:36864
	ds_read_b64_tr_b16 v[98:99], v214 offset:37376
	v_mfma_f32_32x32x16_bf16 v[112:127], v[188:191], v[172:175], v[32:47]
	v_add_f32_e32 v251, v105, v251
	v_add_f32_e32 v252, v106, v252
	v_add_f32_e32 v253, v107, v253
	v_add_f32_e32 v250, v108, v250
	v_cvt_pk_bf16_f32 v162, v100, v101
	v_cvt_pk_bf16_f32 v163, v102, v103
	ds_read_b64_tr_b16 v[100:101], v214 offset:33792
	ds_read_b64_tr_b16 v[102:103], v214 offset:34304
	v_add_f32_e32 v251, v109, v251
	v_add_f32_e32 v252, v110, v252
	v_add_f32_e32 v253, v111, v253
	v_add_f32_e32 v250, v80, v250
	v_cvt_pk_bf16_f32 v10, v104, v105
	v_cvt_pk_bf16_f32 v11, v106, v107
	v_mfma_f32_32x32x16_bf16 v[128:143], v[184:187], v[176:179], v[128:143]
	ds_read_b64_tr_b16 v[104:105], v214 offset:37888
	ds_read_b64_tr_b16 v[106:107], v214 offset:38400
	v_mfma_f32_32x32x16_bf16 v[112:127], v[180:183], v[176:179], v[112:127]
	v_add_f32_e32 v251, v81, v251
	v_add_f32_e32 v252, v82, v252
	v_add_f32_e32 v253, v83, v253
	v_add_f32_e32 v250, v84, v250
	v_cvt_pk_bf16_f32 v12, v108, v109
	v_cvt_pk_bf16_f32 v13, v110, v111
	ds_read_b64_tr_b16 v[108:109], v214 offset:34816
	ds_read_b64_tr_b16 v[110:111], v214 offset:35328
	v_add_f32_e32 v251, v85, v251
	v_add_f32_e32 v252, v86, v252
	v_add_f32_e32 v253, v87, v253
	v_add_f32_e32 v250, v88, v250
	v_cvt_pk_bf16_f32 v6, v80, v81
	v_cvt_pk_bf16_f32 v7, v82, v83
	v_mfma_f32_32x32x16_bf16 v[128:143], v[156:159], v[168:171], v[128:143]
	ds_read_b64_tr_b16 v[80:81], v214 offset:38912
	ds_read_b64_tr_b16 v[82:83], v214 offset:39424
	v_mfma_f32_32x32x16_bf16 v[112:127], v[152:155], v[168:171], v[112:127]
	v_add_f32_e32 v251, v89, v251
	v_add_f32_e32 v252, v90, v252
	v_add_f32_e32 v253, v91, v253
	v_add_f32_e32 v250, v92, v250
	v_cvt_pk_bf16_f32 v8, v84, v85
	v_cvt_pk_bf16_f32 v9, v86, v87
	ds_read_b64_tr_b16 v[84:85], v214 offset:35840
	ds_read_b64_tr_b16 v[86:87], v214 offset:36352
	v_add_f32_e32 v251, v93, v251
	v_add_f32_e32 v252, v94, v252
	v_add_f32_e32 v253, v95, v253
	v_mfma_f32_32x32x16_bf16 v[128:143], v[148:151], v[164:167], v[128:143]
	v_add_f32_e32 v250, v251, v250
	v_cvt_pk_bf16_f32 v2, v88, v89
	v_cvt_pk_bf16_f32 v3, v90, v91
	ds_read_b64_tr_b16 v[88:89], v214 offset:39936
	ds_read_b64_tr_b16 v[90:91], v214 offset:40448
	v_mfma_f32_32x32x16_bf16 v[112:127], v[144:147], v[164:167], v[112:127]
	v_add_f32_e32 v252, v253, v252
	v_add_f32_e32 v144, v252, v250
	v_cvt_pk_bf16_f32 v4, v92, v93
	v_cvt_pk_bf16_f32 v5, v94, v95
	v_lshl_add_u64 v[92:93], v[196:197], 0, s[14:15]
	s_add_i32 s46, s47, s31
	s_mov_b32 s47, m0
	s_mov_b32 m0, s46
	s_nop 0
	global_load_lds_dwordx4 v[92:93], off
	s_mov_b32 m0, s47
	s_add_i32 s46, s45, s42
	s_mov_b32 s47, m0
	s_mov_b32 m0, s46
	s_nop 0
	global_load_lds_dwordx4 v[194:195], off
	s_mov_b32 m0, s47
	v_add_f32_e32 v0, v0, v144
	s_waitcnt lgkmcnt(14)
	v_mfma_f32_32x32x16_bf16 v[48:63], v[160:163], v[210:213], v[48:63]
	v_exp_f32_e32 v128, v128
	v_exp_f32_e32 v129, v129
	v_exp_f32_e32 v130, v130
	v_exp_f32_e32 v131, v131
	s_waitcnt lgkmcnt(12)
	v_mfma_f32_32x32x16_bf16 v[64:79], v[160:163], v[96:99], v[64:79]
	v_exp_f32_e32 v132, v132
	v_exp_f32_e32 v133, v133
	v_exp_f32_e32 v134, v134
	v_exp_f32_e32 v135, v135
	v_add_u32_e32 v96, s44, v208
	ds_read_b128 v[92:95], v96
	ds_read_b128 v[148:151], v96 offset:2048
	v_add_u32_e32 v97, s44, v209
	s_waitcnt lgkmcnt(12)
	v_mfma_f32_32x32x16_bf16 v[48:63], v[10:13], v[100:103], v[48:63]
	v_exp_f32_e32 v136, v136
	v_exp_f32_e32 v137, v137
	v_exp_f32_e32 v138, v138
	v_exp_f32_e32 v139, v139
	ds_read_b128 v[152:155], v97
	ds_read_b128 v[156:159], v97 offset:2048
	s_waitcnt lgkmcnt(12)
	v_mfma_f32_32x32x16_bf16 v[64:79], v[10:13], v[104:107], v[64:79]
	v_exp_f32_e32 v140, v140
	v_exp_f32_e32 v141, v141
	v_exp_f32_e32 v142, v142
	v_exp_f32_e32 v143, v143
	ds_read_b128 v[180:183], v96 offset:4096
	ds_read_b128 v[184:187], v96 offset:6144
	s_waitcnt lgkmcnt(12)
	v_mfma_f32_32x32x16_bf16 v[48:63], v[6:9], v[108:111], v[48:63]
	v_exp_f32_e32 v112, v112
	v_exp_f32_e32 v113, v113
	v_exp_f32_e32 v114, v114
	v_exp_f32_e32 v115, v115
	ds_read_b128 v[188:191], v97 offset:4096
	ds_read_b128 v[144:147], v97 offset:6144
	s_waitcnt lgkmcnt(12)
	v_mfma_f32_32x32x16_bf16 v[64:79], v[6:9], v[80:83], v[64:79]
	v_exp_f32_e32 v116, v116
	v_exp_f32_e32 v117, v117
	v_exp_f32_e32 v118, v118
	v_exp_f32_e32 v119, v119
	s_waitcnt lgkmcnt(10)
	v_mfma_f32_32x32x16_bf16 v[48:63], v[2:5], v[84:87], v[48:63]
	v_exp_f32_e32 v120, v120
	v_exp_f32_e32 v121, v121
	v_exp_f32_e32 v122, v122
	v_exp_f32_e32 v123, v123
	s_waitcnt lgkmcnt(8)
	v_mfma_f32_32x32x16_bf16 v[64:79], v[2:5], v[88:91], v[64:79]
	v_exp_f32_e32 v124, v124
	v_exp_f32_e32 v125, v125
	v_exp_f32_e32 v126, v126
	v_exp_f32_e32 v127, v127
	s_waitcnt vmcnt(4) lgkmcnt(0)
	s_barrier
	v_add_u32_e32 v218, s6, v206
	ds_read_b64_tr_b16 v[210:211], v218 offset:32768
	ds_read_b64_tr_b16 v[212:213], v218 offset:33280
	v_mfma_f32_32x32x16_bf16 v[96:111], v[92:95], v[172:175], v[32:47]
	v_add_f32_e32 v250, v128, v129
	v_add_f32_e32 v251, v130, v131
	v_add_f32_e32 v252, v132, v133
	v_add_f32_e32 v253, v134, v135
	v_add_f32_e32 v250, v136, v250
	v_cvt_pk_bf16_f32 v160, v128, v129
	v_cvt_pk_bf16_f32 v161, v130, v131
	ds_read_b64_tr_b16 v[128:129], v218 offset:36864
	ds_read_b64_tr_b16 v[130:131], v218 offset:37376
	v_mfma_f32_32x32x16_bf16 v[80:95], v[148:151], v[172:175], v[32:47]
	v_add_f32_e32 v251, v137, v251
	v_add_f32_e32 v252, v138, v252
	v_add_f32_e32 v253, v139, v253
	v_add_f32_e32 v250, v140, v250
	v_cvt_pk_bf16_f32 v162, v132, v133
	v_cvt_pk_bf16_f32 v163, v134, v135
	ds_read_b64_tr_b16 v[132:133], v218 offset:33792
	ds_read_b64_tr_b16 v[134:135], v218 offset:34304
	v_mfma_f32_32x32x16_bf16 v[96:111], v[152:155], v[176:179], v[96:111]
	v_add_f32_e32 v251, v141, v251
	v_add_f32_e32 v252, v142, v252
	v_add_f32_e32 v253, v143, v253
	v_add_f32_e32 v250, v112, v250
	v_cvt_pk_bf16_f32 v10, v136, v137
	v_cvt_pk_bf16_f32 v11, v138, v139
	ds_read_b64_tr_b16 v[136:137], v218 offset:37888
	ds_read_b64_tr_b16 v[138:139], v218 offset:38400
	v_mfma_f32_32x32x16_bf16 v[80:95], v[156:159], v[176:179], v[80:95]
	v_add_f32_e32 v251, v113, v251
	v_add_f32_e32 v252, v114, v252
	v_add_f32_e32 v253, v115, v253
	v_add_f32_e32 v250, v116, v250
	v_cvt_pk_bf16_f32 v12, v140, v141
	v_cvt_pk_bf16_f32 v13, v142, v143
	ds_read_b64_tr_b16 v[140:141], v218 offset:34816
	ds_read_b64_tr_b16 v[142:143], v218 offset:35328
	v_mfma_f32_32x32x16_bf16 v[96:111], v[180:183], v[168:171], v[96:111]
	v_add_f32_e32 v251, v117, v251
	v_add_f32_e32 v252, v118, v252
	v_add_f32_e32 v253, v119, v253
	v_add_f32_e32 v250, v120, v250
	v_cvt_pk_bf16_f32 v6, v112, v113
	v_cvt_pk_bf16_f32 v7, v114, v115
	ds_read_b64_tr_b16 v[214:215], v218 offset:38912
	ds_read_b64_tr_b16 v[216:217], v218 offset:39424
	v_mfma_f32_32x32x16_bf16 v[80:95], v[184:187], v[168:171], v[80:95]
	v_add_f32_e32 v251, v121, v251
	v_add_f32_e32 v252, v122, v252
	v_add_f32_e32 v253, v123, v253
	v_add_f32_e32 v250, v124, v250
	v_cvt_pk_bf16_f32 v8, v116, v117
	v_cvt_pk_bf16_f32 v9, v118, v119
	ds_read_b64_tr_b16 v[116:117], v218 offset:35840
	ds_read_b64_tr_b16 v[118:119], v218 offset:36352
	v_mfma_f32_32x32x16_bf16 v[96:111], v[188:191], v[164:167], v[96:111]
	v_add_f32_e32 v251, v125, v251
	v_add_f32_e32 v252, v126, v252
	v_add_f32_e32 v253, v127, v253
	v_add_f32_e32 v250, v251, v250
	v_cvt_pk_bf16_f32 v2, v120, v121
	v_cvt_pk_bf16_f32 v3, v122, v123
	ds_read_b64_tr_b16 v[120:121], v218 offset:39936
	ds_read_b64_tr_b16 v[122:123], v218 offset:40448
	v_mfma_f32_32x32x16_bf16 v[80:95], v[144:147], v[164:167], v[80:95]
	v_add_f32_e32 v252, v253, v252
	v_add_f32_e32 v112, v252, v250
	v_cvt_pk_bf16_f32 v4, v124, v125
	v_cvt_pk_bf16_f32 v5, v126, v127
	s_nop 0
	v_add_f32_e32 v0, v0, v112
	v_lshl_add_u64 v[112:113], v[196:197], 0, s[40:41]
	s_add_i32 s46, s44, s31
	s_mov_b32 s47, m0
	s_mov_b32 m0, s46
	s_nop 0
	global_load_lds_dwordx4 v[112:113], off
	s_mov_b32 m0, s47
	v_lshl_add_u64 v[112:113], v[198:199], 0, s[24:25]
	s_add_i32 s46, s7, s42
	s_mov_b32 s47, m0
	s_mov_b32 m0, s46
	s_nop 0
	global_load_lds_dwordx4 v[112:113], off
	s_mov_b32 m0, s47
	s_waitcnt lgkmcnt(14)
	v_mfma_f32_32x32x16_bf16 v[48:63], v[160:163], v[210:213], v[48:63]
	v_exp_f32_e32 v96, v96
	v_exp_f32_e32 v97, v97
	v_exp_f32_e32 v98, v98
	v_exp_f32_e32 v99, v99
	s_waitcnt lgkmcnt(12)
	v_mfma_f32_32x32x16_bf16 v[64:79], v[160:163], v[128:131], v[64:79]
	v_exp_f32_e32 v100, v100
	v_exp_f32_e32 v101, v101
	v_exp_f32_e32 v102, v102
	v_exp_f32_e32 v103, v103
	v_add_u32_e32 v124, s45, v208
	ds_read_b128 v[112:115], v124
	ds_read_b128 v[188:191], v124 offset:2048
	v_add_u32_e32 v125, s45, v209
	s_waitcnt lgkmcnt(12)
	v_mfma_f32_32x32x16_bf16 v[48:63], v[10:13], v[132:135], v[48:63]
	v_exp_f32_e32 v104, v104
	v_exp_f32_e32 v105, v105
	v_exp_f32_e32 v106, v106
	v_exp_f32_e32 v107, v107
	ds_read_b128 v[184:187], v125
	ds_read_b128 v[180:183], v125 offset:2048
	s_waitcnt lgkmcnt(12)
	v_mfma_f32_32x32x16_bf16 v[64:79], v[10:13], v[136:139], v[64:79]
	v_exp_f32_e32 v108, v108
	v_exp_f32_e32 v109, v109
	v_exp_f32_e32 v110, v110
	v_exp_f32_e32 v111, v111
	ds_read_b128 v[156:159], v124 offset:4096
	ds_read_b128 v[152:155], v124 offset:6144
	s_waitcnt lgkmcnt(12)
	v_mfma_f32_32x32x16_bf16 v[48:63], v[6:9], v[140:143], v[48:63]
	v_exp_f32_e32 v80, v80
	v_exp_f32_e32 v81, v81
	v_exp_f32_e32 v82, v82
	v_exp_f32_e32 v83, v83
	ds_read_b128 v[148:151], v125 offset:4096
	ds_read_b128 v[144:147], v125 offset:6144
	s_waitcnt lgkmcnt(12)
	v_mfma_f32_32x32x16_bf16 v[64:79], v[6:9], v[214:217], v[64:79]
	v_exp_f32_e32 v84, v84
	v_exp_f32_e32 v85, v85
	v_exp_f32_e32 v86, v86
	v_exp_f32_e32 v87, v87
	s_waitcnt lgkmcnt(10)
	v_mfma_f32_32x32x16_bf16 v[48:63], v[2:5], v[116:119], v[48:63]
	v_exp_f32_e32 v88, v88
	v_exp_f32_e32 v89, v89
	v_exp_f32_e32 v90, v90
	v_exp_f32_e32 v91, v91
	s_waitcnt lgkmcnt(8)
	v_mfma_f32_32x32x16_bf16 v[64:79], v[2:5], v[120:123], v[64:79]
	v_exp_f32_e32 v92, v92
	v_exp_f32_e32 v93, v93
	v_exp_f32_e32 v94, v94
	v_exp_f32_e32 v95, v95
	s_waitcnt vmcnt(4) lgkmcnt(0)
	s_barrier
	s_add_i32 s43, s43, 2
	v_lshl_add_u64 v[194:195], v[194:195], 0, s[22:23]
	v_lshl_add_u64 v[196:197], v[196:197], 0, s[22:23]
	v_lshl_add_u64 v[198:199], v[198:199], 0, s[22:23]
	s_mov_b32 s46, s44
	s_mov_b32 s47, s45
	s_mov_b32 s44, s7
	s_cmp_gt_u32 s43, 60
	s_mov_b32 s45, s6
	s_cbranch_scc0 .LBB0_1313
	s_and_b32 s6, s21, 0x3fffffc0
	s_lshl_b32 s6, s6, 2
	s_add_i32 s31, s6, 0
	s_add_i32 s31, s31, 0x10000
	ds_read_b64_tr_b16 v[194:195], v206 offset:49152
	ds_read_b64_tr_b16 v[196:197], v206 offset:49664
	s_waitcnt lgkmcnt(9)
	v_mfma_f32_32x32x16_bf16 v[128:143], v[112:115], v[172:175], v[32:47]
	v_add_f32_e32 v250, v96, v97
	v_add_f32_e32 v251, v98, v99
	v_add_f32_e32 v252, v100, v101
	v_add_f32_e32 v253, v102, v103
	v_add_f32_e32 v250, v104, v250
	v_cvt_pk_bf16_f32 v160, v96, v97
	v_cvt_pk_bf16_f32 v161, v98, v99
	ds_read_b64_tr_b16 v[96:97], v206 offset:53248
	ds_read_b64_tr_b16 v[98:99], v206 offset:53760
	v_add_f32_e32 v251, v105, v251
	v_add_f32_e32 v252, v106, v252
	v_add_f32_e32 v253, v107, v253
	v_add_f32_e32 v250, v108, v250
	v_cvt_pk_bf16_f32 v162, v100, v101
	v_cvt_pk_bf16_f32 v163, v102, v103
	s_waitcnt lgkmcnt(10)
	v_mfma_f32_32x32x16_bf16 v[112:127], v[188:191], v[172:175], v[32:47]
	ds_read_b64_tr_b16 v[100:101], v206 offset:50176
	ds_read_b64_tr_b16 v[102:103], v206 offset:50688
	s_waitcnt lgkmcnt(11)
	v_mfma_f32_32x32x16_bf16 v[128:143], v[184:187], v[176:179], v[128:143]
	v_add_f32_e32 v251, v109, v251
	v_add_f32_e32 v252, v110, v252
	v_add_f32_e32 v253, v111, v253
	v_add_f32_e32 v250, v80, v250
	v_cvt_pk_bf16_f32 v10, v104, v105
	v_cvt_pk_bf16_f32 v11, v106, v107
	ds_read_b64_tr_b16 v[104:105], v206 offset:54272
	ds_read_b64_tr_b16 v[106:107], v206 offset:54784
	v_add_f32_e32 v251, v81, v251
	v_add_f32_e32 v252, v82, v252
	v_add_f32_e32 v253, v83, v253
	v_add_f32_e32 v250, v84, v250
	v_cvt_pk_bf16_f32 v12, v108, v109
	v_cvt_pk_bf16_f32 v13, v110, v111
	s_waitcnt lgkmcnt(12)
	v_mfma_f32_32x32x16_bf16 v[112:127], v[180:183], v[176:179], v[112:127]
	ds_read_b64_tr_b16 v[108:109], v206 offset:51200
	ds_read_b64_tr_b16 v[110:111], v206 offset:51712
	s_waitcnt lgkmcnt(13)
	v_mfma_f32_32x32x16_bf16 v[128:143], v[156:159], v[168:171], v[128:143]
	v_add_f32_e32 v251, v85, v251
	v_add_f32_e32 v252, v86, v252
	v_add_f32_e32 v253, v87, v253
	v_add_f32_e32 v250, v88, v250
	v_cvt_pk_bf16_f32 v6, v80, v81
	v_cvt_pk_bf16_f32 v7, v82, v83
	ds_read_b64_tr_b16 v[80:81], v206 offset:55296
	ds_read_b64_tr_b16 v[82:83], v206 offset:55808
	v_add_f32_e32 v251, v89, v251
	v_add_f32_e32 v252, v90, v252
	v_add_f32_e32 v253, v91, v253
	v_add_f32_e32 v250, v92, v250
	v_cvt_pk_bf16_f32 v8, v84, v85
	v_cvt_pk_bf16_f32 v9, v86, v87
	s_waitcnt lgkmcnt(14)
	v_mfma_f32_32x32x16_bf16 v[112:127], v[152:155], v[168:171], v[112:127]
	ds_read_b64_tr_b16 v[84:85], v206 offset:52224
	ds_read_b64_tr_b16 v[86:87], v206 offset:52736
	s_waitcnt lgkmcnt(14)
	v_mfma_f32_32x32x16_bf16 v[128:143], v[148:151], v[164:167], v[128:143]
	v_add_f32_e32 v251, v93, v251
	v_add_f32_e32 v252, v94, v252
	v_add_f32_e32 v253, v95, v253
	v_add_f32_e32 v250, v251, v250
	v_cvt_pk_bf16_f32 v2, v88, v89
	v_cvt_pk_bf16_f32 v3, v90, v91
	ds_read_b64_tr_b16 v[88:89], v206 offset:56320
	ds_read_b64_tr_b16 v[90:91], v206 offset:56832
	v_add_f32_e32 v252, v253, v252
	v_add_f32_e32 v148, v252, v250
	v_cvt_pk_bf16_f32 v4, v92, v93
	v_cvt_pk_bf16_f32 v5, v94, v95
	v_mfma_f32_32x32x16_bf16 v[112:127], v[144:147], v[164:167], v[112:127]
	s_mov_b64 s[42:43], 0x10c000
	v_lshl_add_u64 v[92:93], v[192:193], 0, s[42:43]
	s_mov_b32 s6, m0
	s_mov_b32 m0, s20
	s_nop 0
	global_load_lds_dwordx4 v[92:93], off
	s_mov_b32 m0, s6
	s_mov_b64 s[6:7], 0x104000
	s_cmp_lg_u32 0, -1
	v_lshl_add_u64 v[92:93], v[14:15], 0, s[6:7]
	s_cselect_b32 s6, 0, 0
	s_add_i32 s7, s6, s8
	s_add_i32 s20, s7, 0xa000
	s_mov_b32 s21, m0
	s_mov_b32 m0, s20
	s_nop 0
	global_load_lds_dwordx4 v[92:93], off
	s_mov_b32 m0, s21
	v_add_f32_e32 v0, v0, v148
	s_waitcnt lgkmcnt(14)
	v_mfma_f32_32x32x16_bf16 v[48:63], v[160:163], v[194:197], v[48:63]
	v_exp_f32_e32 v128, v128
	v_exp_f32_e32 v129, v129
	v_exp_f32_e32 v130, v130
	v_exp_f32_e32 v131, v131
	s_waitcnt lgkmcnt(12)
	v_mfma_f32_32x32x16_bf16 v[64:79], v[160:163], v[96:99], v[64:79]
	v_exp_f32_e32 v132, v132
	v_exp_f32_e32 v133, v133
	v_exp_f32_e32 v134, v134
	v_exp_f32_e32 v135, v135
	ds_read_b128 v[92:95], v208
	ds_read_b128 v[180:183], v208 offset:2048
	s_waitcnt lgkmcnt(12)
	v_mfma_f32_32x32x16_bf16 v[48:63], v[10:13], v[100:103], v[48:63]
	v_exp_f32_e32 v136, v136
	v_exp_f32_e32 v137, v137
	v_exp_f32_e32 v138, v138
	v_exp_f32_e32 v139, v139
	ds_read_b128 v[100:103], v209
	ds_read_b128 v[184:187], v209 offset:2048
	s_waitcnt lgkmcnt(12)
	v_mfma_f32_32x32x16_bf16 v[64:79], v[10:13], v[104:107], v[64:79]
	v_exp_f32_e32 v140, v140
	v_exp_f32_e32 v141, v141
	v_exp_f32_e32 v142, v142
	v_exp_f32_e32 v143, v143
	ds_read_b128 v[104:107], v208 offset:4096
	ds_read_b128 v[188:191], v208 offset:6144
	s_waitcnt lgkmcnt(12)
	v_mfma_f32_32x32x16_bf16 v[48:63], v[6:9], v[108:111], v[48:63]
	v_exp_f32_e32 v112, v112
	v_exp_f32_e32 v113, v113
	v_exp_f32_e32 v114, v114
	v_exp_f32_e32 v115, v115
	ds_read_b128 v[108:111], v209 offset:4096
	ds_read_b128 v[96:99], v209 offset:6144
	s_waitcnt lgkmcnt(12)
	v_mfma_f32_32x32x16_bf16 v[64:79], v[6:9], v[80:83], v[64:79]
	v_exp_f32_e32 v116, v116
	v_exp_f32_e32 v117, v117
	v_exp_f32_e32 v118, v118
	v_exp_f32_e32 v119, v119
	s_waitcnt lgkmcnt(10)
	v_mfma_f32_32x32x16_bf16 v[48:63], v[2:5], v[84:87], v[48:63]
	v_exp_f32_e32 v120, v120
	v_exp_f32_e32 v121, v121
	v_exp_f32_e32 v122, v122
	v_exp_f32_e32 v123, v123
	s_waitcnt lgkmcnt(8)
	v_mfma_f32_32x32x16_bf16 v[64:79], v[2:5], v[88:91], v[64:79]
	v_exp_f32_e32 v124, v124
	v_exp_f32_e32 v125, v125
	v_exp_f32_e32 v126, v126
	v_exp_f32_e32 v127, v127
	s_waitcnt vmcnt(4) lgkmcnt(0)
	s_barrier
	ds_read_b64_tr_b16 v[192:193], v206 offset:57344
	ds_read_b64_tr_b16 v[194:195], v206 offset:57856
	v_add_f32_e32 v250, v128, v129
	v_add_f32_e32 v251, v130, v131
	v_add_f32_e32 v252, v132, v133
	v_add_f32_e32 v253, v134, v135
	v_add_f32_e32 v250, v136, v250
	v_cvt_pk_bf16_f32 v160, v128, v129
	v_cvt_pk_bf16_f32 v161, v130, v131
	s_waitcnt lgkmcnt(9)
	v_mfma_f32_32x32x16_bf16 v[144:159], v[92:95], v[172:175], v[32:47]
	ds_read_b64_tr_b16 v[128:129], v206 offset:61440
	ds_read_b64_tr_b16 v[130:131], v206 offset:61952
	s_waitcnt lgkmcnt(10)
	v_mfma_f32_32x32x16_bf16 v[80:95], v[180:183], v[172:175], v[32:47]
	v_add_f32_e32 v251, v137, v251
	v_add_f32_e32 v252, v138, v252
	v_add_f32_e32 v253, v139, v253
	v_add_f32_e32 v250, v140, v250
	v_cvt_pk_bf16_f32 v162, v132, v133
	v_cvt_pk_bf16_f32 v163, v134, v135
	ds_read_b64_tr_b16 v[132:133], v206 offset:58368
	ds_read_b64_tr_b16 v[134:135], v206 offset:58880
	v_add_f32_e32 v251, v141, v251
	v_add_f32_e32 v252, v142, v252
	v_add_f32_e32 v253, v143, v253
	v_add_f32_e32 v250, v112, v250
	v_cvt_pk_bf16_f32 v10, v136, v137
	v_cvt_pk_bf16_f32 v11, v138, v139
	s_waitcnt lgkmcnt(11)
	v_mfma_f32_32x32x16_bf16 v[144:159], v[100:103], v[176:179], v[144:159]
	ds_read_b64_tr_b16 v[100:101], v206 offset:62464
	ds_read_b64_tr_b16 v[102:103], v206 offset:62976
	s_waitcnt lgkmcnt(12)
	v_mfma_f32_32x32x16_bf16 v[80:95], v[184:187], v[176:179], v[80:95]
	v_add_f32_e32 v251, v113, v251
	v_add_f32_e32 v252, v114, v252
	v_add_f32_e32 v253, v115, v253
	v_add_f32_e32 v250, v116, v250
	v_cvt_pk_bf16_f32 v12, v140, v141
	v_cvt_pk_bf16_f32 v13, v142, v143
	ds_read_b64_tr_b16 v[136:137], v206 offset:59392
	ds_read_b64_tr_b16 v[138:139], v206 offset:59904
	v_add_f32_e32 v251, v117, v251
	v_add_f32_e32 v252, v118, v252
	v_add_f32_e32 v253, v119, v253
	v_add_f32_e32 v250, v120, v250
	v_cvt_pk_bf16_f32 v6, v112, v113
	v_cvt_pk_bf16_f32 v7, v114, v115
	s_waitcnt lgkmcnt(13)
	v_mfma_f32_32x32x16_bf16 v[144:159], v[104:107], v[168:171], v[144:159]
	ds_read_b64_tr_b16 v[104:105], v206 offset:63488
	ds_read_b64_tr_b16 v[106:107], v206 offset:64000
	s_waitcnt lgkmcnt(14)
	v_mfma_f32_32x32x16_bf16 v[80:95], v[188:191], v[168:171], v[80:95]
	v_add_f32_e32 v251, v121, v251
	v_add_f32_e32 v252, v122, v252
	v_add_f32_e32 v253, v123, v253
	v_add_f32_e32 v250, v124, v250
	v_cvt_pk_bf16_f32 v8, v116, v117
	v_cvt_pk_bf16_f32 v9, v118, v119
	ds_read_b64_tr_b16 v[116:117], v206 offset:60416
	ds_read_b64_tr_b16 v[118:119], v206 offset:60928
	v_add_f32_e32 v251, v125, v251
	v_add_f32_e32 v252, v126, v252
	v_add_f32_e32 v253, v127, v253
	v_add_f32_e32 v250, v251, v250
	v_cvt_pk_bf16_f32 v2, v120, v121
	v_cvt_pk_bf16_f32 v3, v122, v123
	s_waitcnt lgkmcnt(14)
	v_mfma_f32_32x32x16_bf16 v[144:159], v[108:111], v[164:167], v[144:159]
	ds_read_b64_tr_b16 v[108:109], v206 offset:64512
	ds_read_b64_tr_b16 v[110:111], v206 offset:65024
	v_mfma_f32_32x32x16_bf16 v[80:95], v[96:99], v[164:167], v[80:95]
	v_add_f32_e32 v252, v253, v252
	v_add_f32_e32 v96, v252, v250
	v_cvt_pk_bf16_f32 v4, v124, v125
	v_cvt_pk_bf16_f32 v5, v126, v127
	s_mov_b64 s[20:21], 0x108000
	v_add_f32_e32 v0, v0, v96
	v_lshl_add_u64 v[96:97], v[14:15], 0, s[20:21]
	s_add_i32 s7, s7, 0xc000
	s_mov_b32 s20, m0
	s_mov_b32 m0, s7
	s_nop 0
	global_load_lds_dwordx4 v[96:97], off
	s_mov_b32 m0, s20
	s_waitcnt lgkmcnt(14)
	v_mfma_f32_32x32x16_bf16 v[48:63], v[160:163], v[192:195], v[48:63]
	v_exp_f32_e32 v144, v144
	v_exp_f32_e32 v145, v145
	v_exp_f32_e32 v146, v146
	v_exp_f32_e32 v147, v147
	s_waitcnt lgkmcnt(12)
	v_mfma_f32_32x32x16_bf16 v[64:79], v[160:163], v[128:131], v[64:79]
	v_exp_f32_e32 v148, v148
	v_exp_f32_e32 v149, v149
	v_exp_f32_e32 v150, v150
	v_exp_f32_e32 v151, v151
	ds_read_b128 v[96:99], v208 offset:8192
	ds_read_b128 v[120:123], v208 offset:10240
	s_waitcnt lgkmcnt(12)
	v_mfma_f32_32x32x16_bf16 v[48:63], v[10:13], v[132:135], v[48:63]
	v_exp_f32_e32 v152, v152
	v_exp_f32_e32 v153, v153
	v_exp_f32_e32 v154, v154
	v_exp_f32_e32 v155, v155
	ds_read_b128 v[124:127], v209 offset:8192
	ds_read_b128 v[180:183], v209 offset:10240
	s_waitcnt lgkmcnt(12)
	v_mfma_f32_32x32x16_bf16 v[64:79], v[10:13], v[100:103], v[64:79]
	v_exp_f32_e32 v156, v156
	v_exp_f32_e32 v157, v157
	v_exp_f32_e32 v158, v158
	v_exp_f32_e32 v159, v159
	ds_read_b128 v[184:187], v208 offset:12288
	ds_read_b128 v[188:191], v208 offset:14336
	s_waitcnt lgkmcnt(12)
	v_mfma_f32_32x32x16_bf16 v[48:63], v[6:9], v[136:139], v[48:63]
	v_exp_f32_e32 v80, v80
	v_exp_f32_e32 v81, v81
	v_exp_f32_e32 v82, v82
	v_exp_f32_e32 v83, v83
	ds_read_b128 v[192:195], v209 offset:12288
	ds_read_b128 v[112:115], v209 offset:14336
	s_waitcnt lgkmcnt(12)
	v_mfma_f32_32x32x16_bf16 v[64:79], v[6:9], v[104:107], v[64:79]
	v_exp_f32_e32 v84, v84
	v_exp_f32_e32 v85, v85
	v_exp_f32_e32 v86, v86
	v_exp_f32_e32 v87, v87
	s_waitcnt lgkmcnt(10)
	v_mfma_f32_32x32x16_bf16 v[48:63], v[2:5], v[116:119], v[48:63]
	v_exp_f32_e32 v88, v88
	v_exp_f32_e32 v89, v89
	v_exp_f32_e32 v90, v90
	v_exp_f32_e32 v91, v91
	s_waitcnt lgkmcnt(8)
	v_mfma_f32_32x32x16_bf16 v[64:79], v[2:5], v[108:111], v[64:79]
	v_exp_f32_e32 v92, v92
	v_exp_f32_e32 v93, v93
	v_exp_f32_e32 v94, v94
	v_exp_f32_e32 v95, v95
	s_waitcnt vmcnt(3) lgkmcnt(0)
	s_barrier
	ds_read_b64_tr_b16 v[116:117], v206 offset:32768
	ds_read_b64_tr_b16 v[118:119], v206 offset:33280
	s_waitcnt lgkmcnt(9)
	v_mfma_f32_32x32x16_bf16 v[128:143], v[96:99], v[172:175], v[32:47]
	v_add_f32_e32 v250, v144, v145
	v_add_f32_e32 v251, v146, v147
	v_add_f32_e32 v252, v148, v149
	v_add_f32_e32 v253, v150, v151
	v_add_f32_e32 v250, v152, v250
	v_cvt_pk_bf16_f32 v160, v144, v145
	v_cvt_pk_bf16_f32 v161, v146, v147
	ds_read_b64_tr_b16 v[144:145], v206 offset:36864
	ds_read_b64_tr_b16 v[146:147], v206 offset:37376
	v_add_f32_e32 v251, v153, v251
	v_add_f32_e32 v252, v154, v252
	v_add_f32_e32 v253, v155, v253
	v_add_f32_e32 v250, v156, v250
	v_cvt_pk_bf16_f32 v162, v148, v149
	v_cvt_pk_bf16_f32 v163, v150, v151
	s_waitcnt lgkmcnt(10)
	v_mfma_f32_32x32x16_bf16 v[96:111], v[120:123], v[172:175], v[32:47]
	ds_read_b64_tr_b16 v[120:121], v206 offset:33792
	ds_read_b64_tr_b16 v[122:123], v206 offset:34304
	s_waitcnt lgkmcnt(11)
	v_mfma_f32_32x32x16_bf16 v[128:143], v[124:127], v[176:179], v[128:143]
	v_add_f32_e32 v251, v157, v251
	v_add_f32_e32 v252, v158, v252
	v_add_f32_e32 v253, v159, v253
	v_add_f32_e32 v250, v80, v250
	v_cvt_pk_bf16_f32 v10, v152, v153
	v_cvt_pk_bf16_f32 v11, v154, v155
	ds_read_b64_tr_b16 v[124:125], v206 offset:37888
	ds_read_b64_tr_b16 v[126:127], v206 offset:38400
	v_add_f32_e32 v251, v81, v251
	v_add_f32_e32 v252, v82, v252
	v_add_f32_e32 v253, v83, v253
	v_add_f32_e32 v250, v84, v250
	v_cvt_pk_bf16_f32 v12, v156, v157
	v_cvt_pk_bf16_f32 v13, v158, v159
	s_waitcnt lgkmcnt(12)
	v_mfma_f32_32x32x16_bf16 v[96:111], v[180:183], v[176:179], v[96:111]
	ds_read_b64_tr_b16 v[148:149], v206 offset:34816
	ds_read_b64_tr_b16 v[150:151], v206 offset:35328
	s_waitcnt lgkmcnt(13)
	v_mfma_f32_32x32x16_bf16 v[128:143], v[184:187], v[168:171], v[128:143]
	v_add_f32_e32 v251, v85, v251
	v_add_f32_e32 v252, v86, v252
	v_add_f32_e32 v253, v87, v253
	v_add_f32_e32 v250, v88, v250
	v_cvt_pk_bf16_f32 v6, v80, v81
	v_cvt_pk_bf16_f32 v7, v82, v83
	ds_read_b64_tr_b16 v[80:81], v206 offset:38912
	ds_read_b64_tr_b16 v[82:83], v206 offset:39424
	v_add_f32_e32 v251, v89, v251
	v_add_f32_e32 v252, v90, v252
	v_add_f32_e32 v253, v91, v253
	v_add_f32_e32 v250, v92, v250
	v_cvt_pk_bf16_f32 v8, v84, v85
	v_cvt_pk_bf16_f32 v9, v86, v87
	s_waitcnt lgkmcnt(14)
	v_mfma_f32_32x32x16_bf16 v[96:111], v[188:191], v[168:171], v[96:111]
	ds_read_b64_tr_b16 v[84:85], v206 offset:35840
	ds_read_b64_tr_b16 v[86:87], v206 offset:36352
	s_waitcnt lgkmcnt(14)
	v_mfma_f32_32x32x16_bf16 v[128:143], v[192:195], v[164:167], v[128:143]
	v_add_f32_e32 v251, v93, v251
	v_add_f32_e32 v252, v94, v252
	v_add_f32_e32 v253, v95, v253
	v_add_f32_e32 v250, v251, v250
	v_cvt_pk_bf16_f32 v2, v88, v89
	v_cvt_pk_bf16_f32 v3, v90, v91
	ds_read_b64_tr_b16 v[88:89], v206 offset:39936
	ds_read_b64_tr_b16 v[90:91], v206 offset:40448
	v_add_f32_e32 v252, v253, v252
	v_add_f32_e32 v152, v252, v250
	v_cvt_pk_bf16_f32 v4, v92, v93
	v_cvt_pk_bf16_f32 v5, v94, v95
	v_mfma_f32_32x32x16_bf16 v[96:111], v[112:115], v[164:167], v[96:111]
	s_add_i32 s6, s6, 0xe000
	v_lshl_add_u64 v[14:15], v[14:15], 0, s[42:43]
	s_add_i32 s8, s8, s6
	s_mov_b32 s7, m0
	s_mov_b32 m0, s8
	s_nop 0
	global_load_lds_dwordx4 v[14:15], off
	s_mov_b32 m0, s7
	v_add_f32_e32 v0, v0, v152
	s_mov_b64 s[80:81], 0x10c000
	s_waitcnt lgkmcnt(14)
	v_mfma_f32_32x32x16_bf16 v[48:63], v[160:163], v[116:119], v[48:63]
	v_exp_f32_e32 v128, v128
	v_exp_f32_e32 v129, v129
	v_exp_f32_e32 v130, v130
	v_exp_f32_e32 v131, v131
	s_waitcnt lgkmcnt(12)
	v_mfma_f32_32x32x16_bf16 v[64:79], v[160:163], v[144:147], v[64:79]
	v_exp_f32_e32 v132, v132
	v_exp_f32_e32 v133, v133
	v_exp_f32_e32 v134, v134
	v_exp_f32_e32 v135, v135
	ds_read_b128 v[92:95], v208 offset:16384
	ds_read_b128 v[152:155], v208 offset:18432
	s_waitcnt lgkmcnt(12)
	v_mfma_f32_32x32x16_bf16 v[48:63], v[10:13], v[120:123], v[48:63]
	v_exp_f32_e32 v136, v136
	v_exp_f32_e32 v137, v137
	v_exp_f32_e32 v138, v138
	v_exp_f32_e32 v139, v139
	ds_read_b128 v[156:159], v209 offset:16384
	ds_read_b128 v[180:183], v209 offset:18432
	s_waitcnt lgkmcnt(12)
	v_mfma_f32_32x32x16_bf16 v[64:79], v[10:13], v[124:127], v[64:79]
	v_exp_f32_e32 v140, v140
	v_exp_f32_e32 v141, v141
	v_exp_f32_e32 v142, v142
	v_exp_f32_e32 v143, v143
	ds_read_b128 v[184:187], v208 offset:20480
	ds_read_b128 v[188:191], v208 offset:22528
	s_waitcnt lgkmcnt(12)
	v_mfma_f32_32x32x16_bf16 v[48:63], v[6:9], v[148:151], v[48:63]
	v_exp_f32_e32 v96, v96
	v_exp_f32_e32 v97, v97
	v_exp_f32_e32 v98, v98
	v_exp_f32_e32 v99, v99
	ds_read_b128 v[148:151], v209 offset:20480
	ds_read_b128 v[144:147], v209 offset:22528
	s_waitcnt lgkmcnt(12)
	v_mfma_f32_32x32x16_bf16 v[64:79], v[6:9], v[80:83], v[64:79]
	v_exp_f32_e32 v100, v100
	v_exp_f32_e32 v101, v101
	v_exp_f32_e32 v102, v102
	v_exp_f32_e32 v103, v103
	s_waitcnt lgkmcnt(10)
	v_mfma_f32_32x32x16_bf16 v[48:63], v[2:5], v[84:87], v[48:63]
	v_exp_f32_e32 v104, v104
	v_exp_f32_e32 v105, v105
	v_exp_f32_e32 v106, v106
	v_exp_f32_e32 v107, v107
	s_waitcnt lgkmcnt(8)
	v_mfma_f32_32x32x16_bf16 v[64:79], v[2:5], v[88:91], v[64:79]
	v_exp_f32_e32 v108, v108
	v_exp_f32_e32 v109, v109
	v_exp_f32_e32 v110, v110
	v_exp_f32_e32 v111, v111
	s_waitcnt vmcnt(2) lgkmcnt(0)
	s_barrier
	ds_read_b64_tr_b16 v[192:193], v206 offset:40960
	ds_read_b64_tr_b16 v[194:195], v206 offset:41472
	v_add_f32_e32 v250, v128, v129
	v_add_f32_e32 v251, v130, v131
	v_add_f32_e32 v252, v132, v133
	v_add_f32_e32 v253, v134, v135
	v_add_f32_e32 v250, v136, v250
	v_cvt_pk_bf16_f32 v160, v128, v129
	v_cvt_pk_bf16_f32 v161, v130, v131
	s_waitcnt lgkmcnt(9)
	v_mfma_f32_32x32x16_bf16 v[112:127], v[92:95], v[172:175], v[32:47]
	ds_read_b64_tr_b16 v[128:129], v206 offset:45056
	ds_read_b64_tr_b16 v[130:131], v206 offset:45568
	s_waitcnt lgkmcnt(10)
	v_mfma_f32_32x32x16_bf16 v[80:95], v[152:155], v[172:175], v[32:47]
	v_add_f32_e32 v251, v137, v251
	v_add_f32_e32 v252, v138, v252
	v_add_f32_e32 v253, v139, v253
	v_add_f32_e32 v250, v140, v250
	v_cvt_pk_bf16_f32 v162, v132, v133
	v_cvt_pk_bf16_f32 v163, v134, v135
	ds_read_b64_tr_b16 v[132:133], v206 offset:41984
	ds_read_b64_tr_b16 v[134:135], v206 offset:42496
	v_add_f32_e32 v251, v141, v251
	v_add_f32_e32 v252, v142, v252
	v_add_f32_e32 v253, v143, v253
	v_add_f32_e32 v250, v96, v250
	v_cvt_pk_bf16_f32 v10, v136, v137
	v_cvt_pk_bf16_f32 v11, v138, v139
	s_waitcnt lgkmcnt(11)
	v_mfma_f32_32x32x16_bf16 v[112:127], v[156:159], v[176:179], v[112:127]
	ds_read_b64_tr_b16 v[136:137], v206 offset:46080
	ds_read_b64_tr_b16 v[138:139], v206 offset:46592
	s_waitcnt lgkmcnt(12)
	v_mfma_f32_32x32x16_bf16 v[80:95], v[180:183], v[176:179], v[80:95]
	v_add_f32_e32 v251, v97, v251
	v_add_f32_e32 v252, v98, v252
	v_add_f32_e32 v253, v99, v253
	v_add_f32_e32 v250, v100, v250
	v_cvt_pk_bf16_f32 v12, v140, v141
	v_cvt_pk_bf16_f32 v13, v142, v143
	ds_read_b64_tr_b16 v[140:141], v206 offset:43008
	ds_read_b64_tr_b16 v[142:143], v206 offset:43520
	v_add_f32_e32 v251, v101, v251
	v_add_f32_e32 v252, v102, v252
	v_add_f32_e32 v253, v103, v253
	v_add_f32_e32 v250, v104, v250
	v_cvt_pk_bf16_f32 v6, v96, v97
	v_cvt_pk_bf16_f32 v7, v98, v99
	s_waitcnt lgkmcnt(13)
	v_mfma_f32_32x32x16_bf16 v[112:127], v[184:187], v[168:171], v[112:127]
	ds_read_b64_tr_b16 v[96:97], v206 offset:47104
	ds_read_b64_tr_b16 v[98:99], v206 offset:47616
	s_waitcnt lgkmcnt(14)
	v_mfma_f32_32x32x16_bf16 v[80:95], v[188:191], v[168:171], v[80:95]
	v_add_f32_e32 v251, v105, v251
	v_add_f32_e32 v252, v106, v252
	v_add_f32_e32 v253, v107, v253
	v_add_f32_e32 v250, v108, v250
	v_cvt_pk_bf16_f32 v8, v100, v101
	v_cvt_pk_bf16_f32 v9, v102, v103
	ds_read_b64_tr_b16 v[100:101], v206 offset:44032
	ds_read_b64_tr_b16 v[102:103], v206 offset:44544
	v_add_f32_e32 v251, v109, v251
	v_add_f32_e32 v252, v110, v252
	v_add_f32_e32 v253, v111, v253
	v_add_f32_e32 v250, v251, v250
	v_cvt_pk_bf16_f32 v2, v104, v105
	v_cvt_pk_bf16_f32 v3, v106, v107
	s_waitcnt lgkmcnt(14)
	v_mfma_f32_32x32x16_bf16 v[112:127], v[148:151], v[164:167], v[112:127]
	ds_read_b64_tr_b16 v[104:105], v206 offset:48128
	ds_read_b64_tr_b16 v[106:107], v206 offset:48640
	v_mfma_f32_32x32x16_bf16 v[80:95], v[144:147], v[164:167], v[80:95]
	v_add_f32_e32 v252, v253, v252
	v_add_f32_e32 v14, v252, v250
	v_cvt_pk_bf16_f32 v4, v108, v109
	v_cvt_pk_bf16_f32 v5, v110, v111
	s_nop 0
	v_add_f32_e32 v185, v0, v14
	s_waitcnt lgkmcnt(14)
	v_mfma_f32_32x32x16_bf16 v[48:63], v[160:163], v[192:195], v[48:63]
	s_nop 0
	v_exp_f32_e32 v112, v112
	v_exp_f32_e32 v113, v113
	v_exp_f32_e32 v114, v114
	v_exp_f32_e32 v115, v115
	s_waitcnt lgkmcnt(12)
	v_mfma_f32_32x32x16_bf16 v[64:79], v[160:163], v[128:131], v[64:79]
	v_exp_f32_e32 v116, v116
	v_exp_f32_e32 v117, v117
	v_exp_f32_e32 v118, v118
	v_exp_f32_e32 v119, v119
	ds_read_b128 v[148:151], v208 offset:24576
	ds_read_b128 v[186:189], v208 offset:26624
	s_waitcnt lgkmcnt(12)
	v_mfma_f32_32x32x16_bf16 v[48:63], v[10:13], v[132:135], v[48:63]
	v_exp_f32_e32 v120, v120
	v_exp_f32_e32 v121, v121
	v_exp_f32_e32 v122, v122
	v_exp_f32_e32 v123, v123
	ds_read_b128 v[190:193], v209 offset:24576
	ds_read_b128 v[194:197], v209 offset:26624
	s_waitcnt lgkmcnt(12)
	v_mfma_f32_32x32x16_bf16 v[64:79], v[10:13], v[136:139], v[64:79]
	v_exp_f32_e32 v124, v124
	v_exp_f32_e32 v125, v125
	v_exp_f32_e32 v126, v126
	v_exp_f32_e32 v127, v127
	ds_read_b128 v[210:213], v208 offset:28672
	ds_read_b128 v[180:183], v208 offset:30720
	s_waitcnt lgkmcnt(12)
	v_mfma_f32_32x32x16_bf16 v[48:63], v[6:9], v[140:143], v[48:63]
	v_exp_f32_e32 v80, v80
	v_exp_f32_e32 v81, v81
	v_exp_f32_e32 v82, v82
	v_exp_f32_e32 v83, v83
	ds_read_b128 v[156:159], v209 offset:28672
	ds_read_b128 v[152:155], v209 offset:30720
	s_waitcnt lgkmcnt(12)
	v_mfma_f32_32x32x16_bf16 v[64:79], v[6:9], v[96:99], v[64:79]
	v_exp_f32_e32 v84, v84
	v_exp_f32_e32 v85, v85
	v_exp_f32_e32 v86, v86
	v_exp_f32_e32 v87, v87
	s_waitcnt lgkmcnt(10)
	v_mfma_f32_32x32x16_bf16 v[48:63], v[2:5], v[100:103], v[48:63]
	v_exp_f32_e32 v88, v88
	v_exp_f32_e32 v89, v89
	v_exp_f32_e32 v90, v90
	v_exp_f32_e32 v91, v91
	s_waitcnt lgkmcnt(8)
	v_mfma_f32_32x32x16_bf16 v[64:79], v[2:5], v[104:107], v[64:79]
	v_exp_f32_e32 v92, v92
	v_exp_f32_e32 v93, v93
	v_exp_f32_e32 v94, v94
	v_exp_f32_e32 v95, v95
	v_lshrrev_b32_e32 v184, 3, v203
	v_or_b32_e32 v2, s4, v184
	v_mov_b32_e32 v3, s5
	v_lshlrev_b64 v[14:15], 11, v[2:3]
	v_lshl_add_u64 v[2:3], s[48:49], 0, v[14:15]
	s_lshl_b32 s8, s26, 1
	v_and_b32_e32 v0, 56, v207
	v_lshl_add_u64 v[2:3], v[2:3], 0, s[8:9]
	v_lshlrev_b32_e32 v0, 1, v0
	v_lshl_add_u64 v[2:3], v[2:3], 0, v[0:1]
	v_add_co_u32_e32 v6, vcc, s67, v2
	s_waitcnt vmcnt(0) lgkmcnt(0)
	s_barrier
	s_nop 1
	v_addc_co_u32_e32 v7, vcc, 0, v3, vcc
	global_load_dwordx4 v[140:143], v[2:3], off
	global_load_dwordx4 v[136:139], v[6:7], off
	v_add_co_u32_e32 v6, vcc, s66, v2
	s_nop 1
	v_addc_co_u32_e32 v7, vcc, 0, v3, vcc
	v_add_co_u32_e32 v2, vcc, s63, v2
	s_nop 1
	v_addc_co_u32_e32 v3, vcc, 0, v3, vcc
	global_load_dwordx4 v[132:135], v[6:7], off
	global_load_dwordx4 v[128:131], v[2:3], off
	ds_read_b64_tr_b16 v[144:145], v206 offset:49152
	ds_read_b64_tr_b16 v[146:147], v206 offset:49664
	v_add_f32_e32 v250, v112, v113
	v_add_f32_e32 v251, v114, v115
	v_add_f32_e32 v252, v116, v117
	v_add_f32_e32 v253, v118, v119
	v_add_f32_e32 v250, v120, v250
	v_cvt_pk_bf16_f32 v160, v112, v113
	v_cvt_pk_bf16_f32 v161, v114, v115
	s_waitcnt lgkmcnt(9)
	v_mfma_f32_32x32x16_bf16 v[96:111], v[148:151], v[172:175], v[32:47]
	ds_read_b64_tr_b16 v[112:113], v206 offset:53248
	ds_read_b64_tr_b16 v[114:115], v206 offset:53760
	v_add_f32_e32 v251, v121, v251
	v_add_f32_e32 v252, v122, v252
	v_add_f32_e32 v253, v123, v253
	v_add_f32_e32 v250, v124, v250
	v_cvt_pk_bf16_f32 v162, v116, v117
	v_cvt_pk_bf16_f32 v163, v118, v119
	s_waitcnt lgkmcnt(10)
	v_mfma_f32_32x32x16_bf16 v[32:47], v[186:189], v[172:175], v[32:47]
	ds_read_b64_tr_b16 v[148:149], v206 offset:50176
	ds_read_b64_tr_b16 v[150:151], v206 offset:50688
	v_add_f32_e32 v251, v125, v251
	v_add_f32_e32 v252, v126, v252
	v_add_f32_e32 v253, v127, v253
	v_add_f32_e32 v250, v80, v250
	v_cvt_pk_bf16_f32 v10, v120, v121
	v_cvt_pk_bf16_f32 v11, v122, v123
	s_waitcnt lgkmcnt(11)
	v_mfma_f32_32x32x16_bf16 v[96:111], v[190:193], v[176:179], v[96:111]
	ds_read_b64_tr_b16 v[116:117], v206 offset:54272
	ds_read_b64_tr_b16 v[118:119], v206 offset:54784
	v_add_f32_e32 v251, v81, v251
	v_add_f32_e32 v252, v82, v252
	v_add_f32_e32 v253, v83, v253
	v_add_f32_e32 v250, v84, v250
	v_cvt_pk_bf16_f32 v12, v124, v125
	v_cvt_pk_bf16_f32 v13, v126, v127
	s_waitcnt lgkmcnt(12)
	v_mfma_f32_32x32x16_bf16 v[32:47], v[194:197], v[176:179], v[32:47]
	ds_read_b64_tr_b16 v[120:121], v206 offset:51200
	ds_read_b64_tr_b16 v[122:123], v206 offset:51712
	v_add_f32_e32 v251, v85, v251
	v_add_f32_e32 v252, v86, v252
	v_add_f32_e32 v253, v87, v253
	v_add_f32_e32 v250, v88, v250
	v_cvt_pk_bf16_f32 v6, v80, v81
	v_cvt_pk_bf16_f32 v7, v82, v83
	s_waitcnt lgkmcnt(13)
	v_mfma_f32_32x32x16_bf16 v[96:111], v[210:213], v[168:171], v[96:111]
	ds_read_b64_tr_b16 v[80:81], v206 offset:55296
	ds_read_b64_tr_b16 v[82:83], v206 offset:55808
	v_add_f32_e32 v251, v89, v251
	v_add_f32_e32 v252, v90, v252
	v_add_f32_e32 v253, v91, v253
	v_add_f32_e32 v250, v92, v250
	v_cvt_pk_bf16_f32 v8, v84, v85
	v_cvt_pk_bf16_f32 v9, v86, v87
	s_waitcnt lgkmcnt(14)
	v_mfma_f32_32x32x16_bf16 v[32:47], v[180:183], v[168:171], v[32:47]
	ds_read_b64_tr_b16 v[124:125], v206 offset:52224
	ds_read_b64_tr_b16 v[126:127], v206 offset:52736
	v_add_f32_e32 v251, v93, v251
	v_add_f32_e32 v252, v94, v252
	v_add_f32_e32 v253, v95, v253
	v_add_f32_e32 v250, v251, v250
	v_cvt_pk_bf16_f32 v2, v88, v89
	v_cvt_pk_bf16_f32 v3, v90, v91
	s_waitcnt lgkmcnt(14)
	v_mfma_f32_32x32x16_bf16 v[96:111], v[156:159], v[164:167], v[96:111]
	ds_read_b64_tr_b16 v[84:85], v206 offset:56320
	ds_read_b64_tr_b16 v[86:87], v206 offset:56832
	v_add_f32_e32 v252, v253, v252
	v_add_f32_e32 v88, v252, v250
	v_cvt_pk_bf16_f32 v4, v92, v93
	v_cvt_pk_bf16_f32 v5, v94, v95
	v_mfma_f32_32x32x16_bf16 v[32:47], v[152:155], v[164:167], v[32:47]
	s_nop 4
	v_exp_f32_e32 v96, v96
	v_exp_f32_e32 v97, v97
	v_exp_f32_e32 v98, v98
	v_exp_f32_e32 v99, v99
	s_nop 0
	v_exp_f32_e32 v100, v100
	v_exp_f32_e32 v101, v101
	v_exp_f32_e32 v102, v102
	v_exp_f32_e32 v103, v103
	s_nop 0
	v_exp_f32_e32 v104, v104
	v_exp_f32_e32 v105, v105
	v_exp_f32_e32 v106, v106
	v_exp_f32_e32 v107, v107
	s_nop 0
	v_exp_f32_e32 v108, v108
	v_exp_f32_e32 v109, v109
	v_exp_f32_e32 v110, v110
	v_exp_f32_e32 v111, v111
	v_exp_f32_e32 v32, v32
	v_exp_f32_e32 v33, v33
	v_exp_f32_e32 v34, v34
	v_exp_f32_e32 v35, v35
	s_nop 0
	v_exp_f32_e32 v36, v36
	v_exp_f32_e32 v37, v37
	v_exp_f32_e32 v38, v38
	v_exp_f32_e32 v39, v39
	s_nop 0
	v_exp_f32_e32 v40, v40
	v_exp_f32_e32 v41, v41
	v_exp_f32_e32 v42, v42
	v_exp_f32_e32 v43, v43
	s_nop 0
	v_exp_f32_e32 v44, v44
	v_exp_f32_e32 v45, v45
	v_exp_f32_e32 v46, v46
	v_exp_f32_e32 v47, v47
	s_waitcnt lgkmcnt(14)
	v_mfma_f32_32x32x16_bf16 v[48:63], v[160:163], v[144:147], v[48:63]
	v_add_f32_e32 v250, v96, v97
	v_add_f32_e32 v251, v98, v99
	v_add_f32_e32 v252, v100, v101
	v_add_f32_e32 v253, v102, v103
	v_add_f32_e32 v250, v104, v250
	v_add_f32_e32 v251, v105, v251
	v_add_f32_e32 v252, v106, v252
	s_waitcnt lgkmcnt(12)
	v_mfma_f32_32x32x16_bf16 v[64:79], v[160:163], v[112:115], v[64:79]
	v_add_f32_e32 v253, v107, v253
	v_add_f32_e32 v250, v108, v250
	v_add_f32_e32 v251, v109, v251
	v_add_f32_e32 v252, v110, v252
	v_add_f32_e32 v253, v111, v253
	v_add_f32_e32 v250, v32, v250
	v_add_f32_e32 v251, v33, v251
	s_waitcnt lgkmcnt(10)
	v_mfma_f32_32x32x16_bf16 v[48:63], v[10:13], v[148:151], v[48:63]
	v_add_f32_e32 v252, v34, v252
	v_add_f32_e32 v253, v35, v253
	v_add_f32_e32 v250, v36, v250
	v_add_f32_e32 v251, v37, v251
	v_add_f32_e32 v252, v38, v252
	v_add_f32_e32 v253, v39, v253
	v_add_f32_e32 v250, v40, v250
	s_waitcnt lgkmcnt(8)
	v_mfma_f32_32x32x16_bf16 v[64:79], v[10:13], v[116:119], v[64:79]
	v_add_f32_e32 v251, v41, v251
	v_add_f32_e32 v252, v42, v252
	v_add_f32_e32 v253, v43, v253
	v_add_f32_e32 v250, v44, v250
	v_add_f32_e32 v251, v45, v251
	v_add_f32_e32 v252, v46, v252
	v_add_f32_e32 v253, v47, v253
	s_waitcnt lgkmcnt(6)
	v_mfma_f32_32x32x16_bf16 v[48:63], v[6:9], v[120:123], v[48:63]
	v_add_f32_e32 v250, v251, v250
	v_add_f32_e32 v252, v253, v252
	v_add_f32_e32 v89, v252, v250
	v_add_f32_e32 v88, v185, v88
	v_add_f32_e32 v88, v88, v89
	v_cvt_pk_bf16_f32 v90, v96, v97
	v_cvt_pk_bf16_f32 v91, v98, v99
	s_waitcnt lgkmcnt(4)
	v_mfma_f32_32x32x16_bf16 v[64:79], v[6:9], v[80:83], v[64:79]
	v_cvt_pk_bf16_f32 v92, v100, v101
	v_cvt_pk_bf16_f32 v93, v102, v103
	v_cvt_pk_bf16_f32 v10, v104, v105
	v_cvt_pk_bf16_f32 v11, v106, v107
	v_cvt_pk_bf16_f32 v12, v108, v109
	v_cvt_pk_bf16_f32 v13, v110, v111
	v_cvt_pk_bf16_f32 v6, v32, v33
	s_waitcnt lgkmcnt(2)
	v_mfma_f32_32x32x16_bf16 v[48:63], v[2:5], v[124:127], v[48:63]
	v_cvt_pk_bf16_f32 v7, v34, v35
	v_cvt_pk_bf16_f32 v8, v36, v37
	v_cvt_pk_bf16_f32 v9, v38, v39
	v_cvt_pk_bf16_f32 v32, v40, v41
	v_cvt_pk_bf16_f32 v33, v42, v43
	v_cvt_pk_bf16_f32 v34, v44, v45
	v_cvt_pk_bf16_f32 v35, v46, v47
	s_waitcnt lgkmcnt(0)
	v_mfma_f32_32x32x16_bf16 v[64:79], v[2:5], v[84:87], v[64:79]
	v_add_u32_e32 v2, s6, v204
	v_add3_u32 v84, v2, v202, v205
	ds_read_b64_tr_b16 v[2:3],v84 offset:0
	ds_read_b64_tr_b16 v[4:5],v84 offset:512
	ds_read_b64_tr_b16 v[36:37],v84 offset:1024
	ds_read_b64_tr_b16 v[38:39],v84 offset:1536
	ds_read_b64_tr_b16 v[40:41],v84 offset:2048
	ds_read_b64_tr_b16 v[42:43],v84 offset:2560
	ds_read_b64_tr_b16 v[44:45],v84 offset:3072
	ds_read_b64_tr_b16 v[46:47],v84 offset:3584
	s_waitcnt lgkmcnt(0)
	s_nop 0
	v_mfma_f32_32x32x16_bf16 v[48:63], v[90:93], v[2:5], v[48:63]
	ds_read_b64_tr_b16 v[2:3],v84 offset:4096
	ds_read_b64_tr_b16 v[4:5],v84 offset:4608
	v_mfma_f32_32x32x16_bf16 v[48:63], v[10:13], v[36:39], v[48:63]
	ds_read_b64_tr_b16 v[36:37],v84 offset:5120
	ds_read_b64_tr_b16 v[38:39],v84 offset:5632
	v_mfma_f32_32x32x16_bf16 v[48:63], v[6:9], v[40:43], v[48:63]
	ds_read_b64_tr_b16 v[40:41],v84 offset:6144
	ds_read_b64_tr_b16 v[42:43],v84 offset:6656
	ds_read_b64_tr_b16 v[80:81],v84 offset:7168
	ds_read_b64_tr_b16 v[82:83],v84 offset:7680
	s_waitcnt lgkmcnt(0)
	v_mfma_f32_32x32x16_bf16 v[48:63], v[32:35], v[44:47], v[48:63]
	v_mfma_f32_32x32x16_bf16 v[64:79], v[90:93], v[2:5], v[64:79]
	v_mov_b32_e32 v2, v88
	s_nop 1
	v_permlane32_swap_b32_e32 v88, v2
	v_cmp_gt_u32_e32 vcc, 32, v203
	v_mfma_f32_32x32x16_bf16 v[64:79], v[10:13], v[36:39], v[64:79]
	v_mfma_f32_32x32x16_bf16 v[64:79], v[6:9], v[40:43], v[64:79]
	v_mfma_f32_32x32x16_bf16 v[64:79], v[32:35], v[80:83], v[64:79]
	s_and_saveexec_b64 s[6:7], vcc
	v_lshl_add_u32 v3, v200, 2, s31
	v_add_f32_e32 v2, v88, v2
	ds_write_b32 v3, v2 offset:128
	s_or_b64 exec, exec, s[6:7]
	s_waitcnt lgkmcnt(0)
	v_lshl_add_u32 v10, v201, 4, s31
	ds_read_b128 v[2:5], v10 offset:128
	ds_read_b128 v[6:9], v10 offset:160
	s_lshl_b32 s6, s27, 12
	s_add_i32 s6, s6, 0
	s_add_i32 s6, s6, 0x10800
	s_waitcnt lgkmcnt(1)
	v_rcp_f32_e32 v11, v2
	v_rcp_f32_e32 v12, v3
	v_rcp_f32_e32 v13, v4
	v_rcp_f32_e32 v32, v5
	s_waitcnt lgkmcnt(0)
	v_rcp_f32_e32 v33, v6
	ds_read_b128 v[2:5], v10 offset:192
	v_rcp_f32_e32 v34, v7
	v_rcp_f32_e32 v35, v8
	v_rcp_f32_e32 v36, v9
	ds_read_b128 v[6:9], v10 offset:224
	v_lshlrev_b32_e32 v10, 9, v201
	v_lshlrev_b32_e32 v37, 1, v200
	v_add3_u32 v10, s6, v10, v37
	v_mul_f32_e32 v37, v48, v11
	v_mul_f32_e32 v11, v64, v11
	v_cvt_pk_bf16_f32 v11, v11, s0
	ds_write_b16 v10, v11 offset:64
	v_mul_f32_e32 v11, v49, v12
	v_cvt_pk_bf16_f32 v11, v11, s0
	ds_write_b16 v10, v11 offset:128
	v_mul_f32_e32 v11, v65, v12
	v_cvt_pk_bf16_f32 v11, v11, s0
	ds_write_b16 v10, v11 offset:192
	v_mul_f32_e32 v11, v50, v13
	v_cvt_pk_bf16_f32 v11, v11, s0
	ds_write_b16 v10, v11 offset:256
	v_mul_f32_e32 v11, v66, v13
	v_cvt_pk_bf16_f32 v11, v11, s0
	ds_write_b16 v10, v11 offset:320
	v_mul_f32_e32 v11, v51, v32
	v_cvt_pk_bf16_f32 v11, v11, s0
	ds_write_b16 v10, v11 offset:384
	v_mul_f32_e32 v11, v67, v32
	v_cvt_pk_bf16_f32 v11, v11, s0
	ds_write_b16 v10, v11 offset:448
	v_mul_f32_e32 v11, v52, v33
	v_cvt_pk_bf16_f32 v11, v11, s0
	ds_write_b16 v10, v11 offset:1024
	v_mul_f32_e32 v11, v68, v33
	v_cvt_pk_bf16_f32 v11, v11, s0
	ds_write_b16 v10, v11 offset:1088
	v_mul_f32_e32 v11, v53, v34
	v_cvt_pk_bf16_f32 v11, v11, s0
	ds_write_b16 v10, v11 offset:1152
	v_mul_f32_e32 v11, v69, v34
	v_cvt_pk_bf16_f32 v11, v11, s0
	ds_write_b16 v10, v11 offset:1216
	v_mul_f32_e32 v11, v54, v35
	v_cvt_pk_bf16_f32 v11, v11, s0
	ds_write_b16 v10, v11 offset:1280
	v_mul_f32_e32 v11, v70, v35
	v_cvt_pk_bf16_f32 v11, v11, s0
	s_waitcnt lgkmcnt(13)
	v_rcp_f32_e32 v2, v2
	ds_write_b16 v10, v11 offset:1344
	v_mul_f32_e32 v11, v55, v36
	v_cvt_pk_bf16_f32 v11, v11, s0
	v_rcp_f32_e32 v3, v3
	ds_write_b16 v10, v11 offset:1408
	v_mul_f32_e32 v11, v71, v36
	v_cvt_pk_bf16_f32 v11, v11, s0
	ds_write_b16 v10, v11 offset:1472
	v_mul_f32_e32 v11, v56, v2
	v_mul_f32_e32 v2, v72, v2
	v_cvt_pk_bf16_f32 v2, v2, s0
	v_rcp_f32_e32 v4, v4
	ds_write_b16 v10, v2 offset:2112
	v_mul_f32_e32 v2, v57, v3
	v_cvt_pk_bf16_f32 v2, v2, s0
	ds_write_b16 v10, v2 offset:2176
	v_mul_f32_e32 v2, v73, v3
	v_cvt_pk_bf16_f32 v2, v2, s0
	v_rcp_f32_e32 v5, v5
	ds_write_b16 v10, v2 offset:2240
	v_mul_f32_e32 v2, v58, v4
	v_cvt_pk_bf16_f32 v2, v2, s0
	ds_write_b16 v10, v2 offset:2304
	v_mul_f32_e32 v2, v74, v4
	v_cvt_pk_bf16_f32 v2, v2, s0
	s_waitcnt lgkmcnt(14)
	v_rcp_f32_e32 v6, v6
	ds_write_b16 v10, v2 offset:2368
	v_mul_f32_e32 v2, v59, v5
	v_cvt_pk_bf16_f32 v2, v2, s0
	ds_write_b16 v10, v2 offset:2432
	v_mul_f32_e32 v2, v75, v5
	v_cvt_pk_bf16_f32 v2, v2, s0
	v_rcp_f32_e32 v7, v7
	ds_write_b16 v10, v2 offset:2496
	v_mul_f32_e32 v2, v60, v6
	v_cvt_pk_bf16_f32 v2, v2, s0
	ds_write_b16 v10, v2 offset:3072
	v_mul_f32_e32 v2, v76, v6
	v_cvt_pk_bf16_f32 v2, v2, s0
	v_rcp_f32_e32 v8, v8
	ds_write_b16 v10, v2 offset:3136
	v_mul_f32_e32 v2, v61, v7
	v_cvt_pk_bf16_f32 v2, v2, s0
	ds_write_b16 v10, v2 offset:3200
	v_mul_f32_e32 v2, v77, v7
	v_cvt_pk_bf16_f32 v2, v2, s0
	v_rcp_f32_e32 v9, v9
	ds_write_b16 v10, v2 offset:3264
	v_mul_f32_e32 v2, v62, v8
	v_cvt_pk_bf16_f32 v2, v2, s0
	ds_write_b16 v10, v2 offset:3328
	v_mul_f32_e32 v2, v78, v8
	v_cvt_pk_bf16_f32 v2, v2, s0
	ds_write_b16 v10, v2 offset:3392
	v_mul_f32_e32 v2, v63, v9
	s_waitcnt vmcnt(3)
	v_lshlrev_b32_e32 v12, 16, v140
	v_cvt_pk_bf16_f32 v2, v2, s0
	v_and_b32_e32 v13, 0xffff0000, v140
	v_mul_f32_e32 v4, 0xbfb8aa3b, v12
	ds_write_b16 v10, v2 offset:3456
	v_mul_f32_e32 v2, v79, v9
	v_exp_f32_e32 v8, v4
	v_mul_f32_e32 v4, 0xbfb8aa3b, v13
	v_cvt_pk_bf16_f32 v37, v37, s0
	v_cvt_pk_bf16_f32 v11, v11, s0
	v_cvt_pk_bf16_f32 v2, v2, s0
	v_add_u32_e32 v36, s6, v0
	s_add_u32 s6, s50, s8
	v_exp_f32_e32 v9, v4
	ds_write_b16 v10, v37
	ds_write_b16 v10, v11 offset:2048
	ds_write_b16 v10, v2 offset:3520
	s_addc_u32 s7, s51, 0
	s_waitcnt lgkmcnt(0)
	v_lshl_add_u64 v[2:3], s[6:7], 0, v[0:1]
	v_lshl_add_u32 v0, v184, 7, v36
	ds_read_b128 v[4:7], v0
	v_add_f32_e32 v0, 1.0, v8
	v_rcp_f32_e32 v32, v0
	v_add_f32_e32 v0, 1.0, v9
	v_rcp_f32_e32 v33, v0
	s_waitcnt lgkmcnt(0)
	v_lshlrev_b32_e32 v34, 16, v4
	v_and_b32_e32 v35, 0xffff0000, v4
	v_or_b32_e32 v0, 8, v184
	v_pk_mul_f32 v[12:13], v[32:33], v[12:13]
	v_lshlrev_b32_e32 v32, 16, v141
	v_and_b32_e32 v33, 0xffff0000, v141
	v_mul_f32_e32 v4, 0xbfb8aa3b, v32
	v_exp_f32_e32 v4, v4
	v_mul_f32_e32 v37, 0xbfb8aa3b, v33
	v_exp_f32_e32 v37, v37
	v_pk_mul_f32 v[12:13], v[12:13], v[34:35]
	v_add_f32_e32 v4, 1.0, v4
	v_rcp_f32_e32 v34, v4
	v_add_f32_e32 v4, 1.0, v37
	v_rcp_f32_e32 v35, v4
	v_cvt_pk_bf16_f32 v4, v12, v13
	v_lshlrev_b32_e32 v12, 16, v5
	v_and_b32_e32 v13, 0xffff0000, v5
	v_pk_mul_f32 v[32:33], v[34:35], v[32:33]
	v_lshlrev_b32_e32 v34, 16, v142
	v_and_b32_e32 v35, 0xffff0000, v142
	v_mul_f32_e32 v5, 0xbfb8aa3b, v34
	v_exp_f32_e32 v5, v5
	v_mul_f32_e32 v37, 0xbfb8aa3b, v35
	v_exp_f32_e32 v37, v37
	v_pk_mul_f32 v[12:13], v[32:33], v[12:13]
	v_add_f32_e32 v5, 1.0, v5
	v_rcp_f32_e32 v32, v5
	v_add_f32_e32 v5, 1.0, v37
	v_rcp_f32_e32 v33, v5
	v_cvt_pk_bf16_f32 v5, v12, v13
	v_lshlrev_b32_e32 v12, 16, v6
	v_and_b32_e32 v13, 0xffff0000, v6
	v_pk_mul_f32 v[32:33], v[32:33], v[34:35]
	v_lshlrev_b32_e32 v34, 16, v143
	v_and_b32_e32 v35, 0xffff0000, v143
	v_mul_f32_e32 v6, 0xbfb8aa3b, v34
	v_exp_f32_e32 v6, v6
	v_mul_f32_e32 v37, 0xbfb8aa3b, v35
	v_exp_f32_e32 v37, v37
	v_pk_mul_f32 v[12:13], v[32:33], v[12:13]
	v_add_f32_e32 v6, 1.0, v6
	v_rcp_f32_e32 v32, v6
	v_add_f32_e32 v6, 1.0, v37
	v_rcp_f32_e32 v33, v6
	v_cvt_pk_bf16_f32 v6, v12, v13
	v_lshlrev_b32_e32 v12, 16, v7
	v_and_b32_e32 v13, 0xffff0000, v7
	v_pk_mul_f32 v[32:33], v[32:33], v[34:35]
	v_lshl_add_u32 v8, v0, 7, v36
	v_pk_mul_f32 v[12:13], v[32:33], v[12:13]
	ds_read_b128 v[8:11], v8
	v_cvt_pk_bf16_f32 v7, v12, v13
	v_lshl_add_u64 v[12:13], v[2:3], 0, v[14:15]
	global_store_dwordx4 v[12:13], v[4:7], off
	s_waitcnt lgkmcnt(0)
	v_lshlrev_b32_e32 v14, 16, v8
	s_waitcnt vmcnt(3)
	v_lshlrev_b32_e32 v6, 16, v136
	v_and_b32_e32 v7, 0xffff0000, v136
	v_mul_f32_e32 v4, 0xbfb8aa3b, v6
	v_exp_f32_e32 v5, v4
	v_mul_f32_e32 v4, 0xbfb8aa3b, v7
	v_exp_f32_e32 v13, v4
	v_or_b32_e32 v4, s4, v0
	v_add_f32_e32 v0, 1.0, v5
	v_rcp_f32_e32 v12, v0
	v_add_f32_e32 v0, 1.0, v13
	v_rcp_f32_e32 v13, v0
	v_and_b32_e32 v15, 0xffff0000, v8
	v_mov_b32_e32 v5, s5
	v_pk_mul_f32 v[6:7], v[12:13], v[6:7]
	v_lshlrev_b32_e32 v12, 16, v137
	v_and_b32_e32 v13, 0xffff0000, v137
	v_mul_f32_e32 v0, 0xbfb8aa3b, v12
	v_exp_f32_e32 v0, v0
	v_mul_f32_e32 v8, 0xbfb8aa3b, v13
	v_exp_f32_e32 v8, v8
	v_pk_mul_f32 v[6:7], v[6:7], v[14:15]
	v_add_f32_e32 v0, 1.0, v0
	v_rcp_f32_e32 v14, v0
	v_add_f32_e32 v0, 1.0, v8
	v_rcp_f32_e32 v15, v0
	v_cvt_pk_bf16_f32 v6, v6, v7
	v_lshlrev_b32_e32 v8, 16, v9
	v_and_b32_e32 v9, 0xffff0000, v9
	v_pk_mul_f32 v[12:13], v[14:15], v[12:13]
	v_lshlrev_b32_e32 v14, 16, v138
	v_and_b32_e32 v15, 0xffff0000, v138
	v_mul_f32_e32 v0, 0xbfb8aa3b, v14
	v_exp_f32_e32 v0, v0
	v_mul_f32_e32 v7, 0xbfb8aa3b, v15
	v_exp_f32_e32 v7, v7
	v_pk_mul_f32 v[8:9], v[12:13], v[8:9]
	v_add_f32_e32 v0, 1.0, v0
	v_rcp_f32_e32 v12, v0
	v_add_f32_e32 v0, 1.0, v7
	v_rcp_f32_e32 v13, v0
	v_cvt_pk_bf16_f32 v7, v8, v9
	v_lshlrev_b32_e32 v8, 16, v10
	v_and_b32_e32 v9, 0xffff0000, v10
	v_pk_mul_f32 v[12:13], v[12:13], v[14:15]
	v_lshlrev_b32_e32 v14, 16, v139
	v_and_b32_e32 v15, 0xffff0000, v139
	v_mul_f32_e32 v0, 0xbfb8aa3b, v14
	v_exp_f32_e32 v0, v0
	v_mul_f32_e32 v10, 0xbfb8aa3b, v15
	v_exp_f32_e32 v10, v10
	v_pk_mul_f32 v[8:9], v[12:13], v[8:9]
	v_add_f32_e32 v0, 1.0, v0
	v_rcp_f32_e32 v12, v0
	v_add_f32_e32 v0, 1.0, v10
	v_rcp_f32_e32 v13, v0
	v_lshlrev_b32_e32 v10, 16, v11
	v_and_b32_e32 v11, 0xffff0000, v11
	v_cvt_pk_bf16_f32 v8, v8, v9
	v_pk_mul_f32 v[12:13], v[12:13], v[14:15]
	v_or_b32_e32 v0, 16, v184
	v_pk_mul_f32 v[10:11], v[12:13], v[10:11]
	s_waitcnt vmcnt(2)
	v_lshlrev_b32_e32 v14, 16, v132
	v_cvt_pk_bf16_f32 v9, v10, v11
	v_lshlrev_b64 v[10:11], 11, v[4:5]
	v_lshl_add_u64 v[10:11], v[2:3], 0, v[10:11]
	v_lshl_add_u32 v4, v0, 7, v36
	global_store_dwordx4 v[10:11], v[6:9], off
	ds_read_b128 v[6:9], v4
	v_and_b32_e32 v15, 0xffff0000, v132
	v_mul_f32_e32 v4, 0xbfb8aa3b, v14
	v_exp_f32_e32 v10, v4
	v_mul_f32_e32 v4, 0xbfb8aa3b, v15
	v_exp_f32_e32 v11, v4
	v_or_b32_e32 v4, s4, v0
	v_add_f32_e32 v0, 1.0, v10
	v_rcp_f32_e32 v32, v0
	v_add_f32_e32 v0, 1.0, v11
	v_rcp_f32_e32 v33, v0
	v_or_b32_e32 v0, 24, v184
	s_waitcnt lgkmcnt(0)
	v_lshlrev_b32_e32 v34, 16, v6
	v_and_b32_e32 v35, 0xffff0000, v6
	v_pk_mul_f32 v[14:15], v[32:33], v[14:15]
	v_lshlrev_b32_e32 v32, 16, v133
	v_and_b32_e32 v33, 0xffff0000, v133
	v_mul_f32_e32 v6, 0xbfb8aa3b, v32
	v_lshl_add_u32 v10, v0, 7, v36
	v_exp_f32_e32 v6, v6
	v_mul_f32_e32 v36, 0xbfb8aa3b, v33
	v_exp_f32_e32 v36, v36
	v_pk_mul_f32 v[14:15], v[14:15], v[34:35]
	v_add_f32_e32 v6, 1.0, v6
	v_rcp_f32_e32 v34, v6
	v_add_f32_e32 v6, 1.0, v36
	v_rcp_f32_e32 v35, v6
	v_cvt_pk_bf16_f32 v6, v14, v15
	v_lshlrev_b32_e32 v14, 16, v7
	v_and_b32_e32 v15, 0xffff0000, v7
	v_pk_mul_f32 v[32:33], v[34:35], v[32:33]
	v_lshlrev_b32_e32 v34, 16, v134
	v_and_b32_e32 v35, 0xffff0000, v134
	v_mul_f32_e32 v7, 0xbfb8aa3b, v34
	v_exp_f32_e32 v7, v7
	v_mul_f32_e32 v36, 0xbfb8aa3b, v35
	v_exp_f32_e32 v36, v36
	v_pk_mul_f32 v[14:15], v[32:33], v[14:15]
	v_add_f32_e32 v7, 1.0, v7
	v_rcp_f32_e32 v32, v7
	v_add_f32_e32 v7, 1.0, v36
	v_rcp_f32_e32 v33, v7
	v_cvt_pk_bf16_f32 v7, v14, v15
	v_lshlrev_b32_e32 v14, 16, v8
	v_and_b32_e32 v15, 0xffff0000, v8
	v_pk_mul_f32 v[32:33], v[32:33], v[34:35]
	v_lshlrev_b32_e32 v34, 16, v135
	v_and_b32_e32 v35, 0xffff0000, v135
	v_mul_f32_e32 v8, 0xbfb8aa3b, v34
	v_exp_f32_e32 v8, v8
	v_mul_f32_e32 v36, 0xbfb8aa3b, v35
	v_exp_f32_e32 v36, v36
	v_pk_mul_f32 v[14:15], v[32:33], v[14:15]
	v_add_f32_e32 v8, 1.0, v8
	v_rcp_f32_e32 v32, v8
	v_add_f32_e32 v8, 1.0, v36
	v_rcp_f32_e32 v33, v8
	v_cvt_pk_bf16_f32 v8, v14, v15
	v_lshlrev_b32_e32 v14, 16, v9
	v_and_b32_e32 v15, 0xffff0000, v9
	v_pk_mul_f32 v[32:33], v[32:33], v[34:35]
	ds_read_b128 v[10:13], v10
	v_pk_mul_f32 v[14:15], v[32:33], v[14:15]
	s_waitcnt vmcnt(2)
	v_lshlrev_b32_e32 v32, 16, v128
	v_cvt_pk_bf16_f32 v9, v14, v15
	v_lshlrev_b64 v[14:15], 11, v[4:5]
	v_and_b32_e32 v33, 0xffff0000, v128
	v_mul_f32_e32 v4, 0xbfb8aa3b, v32
	v_exp_f32_e32 v4, v4
	v_mul_f32_e32 v34, 0xbfb8aa3b, v33
	v_exp_f32_e32 v34, v34
	v_lshl_add_u64 v[14:15], v[2:3], 0, v[14:15]
	v_add_f32_e32 v4, 1.0, v4
	global_store_dwordx4 v[14:15], v[6:9], off
	v_lshlrev_b32_e32 v14, 16, v129
	v_and_b32_e32 v15, 0xffff0000, v129
	v_rcp_f32_e32 v6, v4
	v_add_f32_e32 v4, 1.0, v34
	v_rcp_f32_e32 v7, v4
	v_or_b32_e32 v4, s4, v0
	v_mul_f32_e32 v0, 0xbfb8aa3b, v14
	s_waitcnt lgkmcnt(0)
	v_lshlrev_b32_e32 v8, 16, v10
	v_and_b32_e32 v9, 0xffff0000, v10
	v_exp_f32_e32 v0, v0
	v_mul_f32_e32 v10, 0xbfb8aa3b, v15
	v_exp_f32_e32 v10, v10
	v_pk_mul_f32 v[6:7], v[6:7], v[32:33]
	v_add_f32_e32 v0, 1.0, v0
	v_pk_mul_f32 v[6:7], v[6:7], v[8:9]
	v_rcp_f32_e32 v8, v0
	v_add_f32_e32 v0, 1.0, v10
	v_rcp_f32_e32 v9, v0
	v_cvt_pk_bf16_f32 v6, v6, v7
	v_lshlrev_b32_e32 v10, 16, v11
	v_and_b32_e32 v11, 0xffff0000, v11
	v_pk_mul_f32 v[8:9], v[8:9], v[14:15]
	v_lshlrev_b32_e32 v14, 16, v130
	v_and_b32_e32 v15, 0xffff0000, v130
	v_mul_f32_e32 v0, 0xbfb8aa3b, v14
	v_exp_f32_e32 v0, v0
	v_mul_f32_e32 v7, 0xbfb8aa3b, v15
	v_exp_f32_e32 v7, v7
	v_pk_mul_f32 v[8:9], v[8:9], v[10:11]
	v_add_f32_e32 v0, 1.0, v0
	v_rcp_f32_e32 v10, v0
	v_add_f32_e32 v0, 1.0, v7
	v_rcp_f32_e32 v11, v0
	v_cvt_pk_bf16_f32 v7, v8, v9
	v_lshlrev_b32_e32 v8, 16, v12
	v_and_b32_e32 v9, 0xffff0000, v12
	v_pk_mul_f32 v[10:11], v[10:11], v[14:15]
	v_lshlrev_b32_e32 v14, 16, v131
	v_and_b32_e32 v15, 0xffff0000, v131
	v_mul_f32_e32 v0, 0xbfb8aa3b, v14
	v_exp_f32_e32 v0, v0
	v_mul_f32_e32 v12, 0xbfb8aa3b, v15
	v_exp_f32_e32 v12, v12
	v_pk_mul_f32 v[8:9], v[10:11], v[8:9]
	v_add_f32_e32 v0, 1.0, v0
	v_rcp_f32_e32 v10, v0
	v_add_f32_e32 v0, 1.0, v12
	v_rcp_f32_e32 v11, v0
	v_lshlrev_b32_e32 v12, 16, v13
	v_and_b32_e32 v13, 0xffff0000, v13
	v_lshlrev_b64 v[4:5], 11, v[4:5]
	v_pk_mul_f32 v[10:11], v[10:11], v[14:15]
	v_cvt_pk_bf16_f32 v8, v8, v9
	v_pk_mul_f32 v[10:11], v[10:11], v[12:13]
	v_lshl_add_u64 v[2:3], v[2:3], 0, v[4:5]
	v_cvt_pk_bf16_f32 v9, v10, v11
	global_store_dwordx4 v[2:3], v[6:9], off
	s_waitcnt vmcnt(0) lgkmcnt(0)
	s_barrier
	s_mov_b64 s[4:5], 0
